# first xcd barrier: the 16 census loads issued together and waited once (prologue de-serialisation)
# speedup vs baseline: 1.0033x; 1.0027x over previous
; __device__ __forceinline__ unsigned xb_ld(unsigned* p)              { return __hip_atomic_load(p, __ATOMIC_RELAXED, __HIP_MEMORY_SCOPE_AGENT); }
; __device__ __forceinline__ void xcd_barrier_complete(unsigned* bar, unsigned x, unsigned& nloc, unsigned& nx) {
;     ...
;     for (;;) {
;         sum = 0u; cnt = 0u; mine = 0u;
; #pragma unroll
;         for (unsigned j = 0; j < 16; ++j) { const unsigned c = xb_ld(&bar[XB_XCNT(j)]); sum += c; cnt += (c > 0u) ? 1u : 0u; mine = (j == x) ? c : mine; }
;         if (sum == G) break;
.LBB0_582:
	v_readlane_b32 s2, v253, 43
	v_readlane_b32 s3, v253, 44
	global_load_dword v0, v129, s[96:97] sc1
	s_mov_b64 s[4:5], -1
	s_nop 2
	global_load_dword v1, v129, s[2:3] sc1
	v_readlane_b32 s2, v253, 45
	v_readlane_b32 s3, v253, 46
	s_nop 4
	global_load_dword v2, v129, s[2:3] sc1
	v_readlane_b32 s2, v253, 47
	v_readlane_b32 s3, v253, 48
	s_nop 4
	global_load_dword v3, v129, s[2:3] sc1
	v_readlane_b32 s2, v253, 49
	v_readlane_b32 s3, v253, 50
	s_nop 4
	global_load_dword v4, v129, s[2:3] sc1
	v_readlane_b32 s2, v253, 51
	v_readlane_b32 s3, v253, 52
	s_nop 4
	global_load_dword v5, v129, s[2:3] sc1
	v_readlane_b32 s2, v253, 53
	v_readlane_b32 s3, v253, 54
	s_nop 4
	global_load_dword v6, v129, s[2:3] sc1
	v_readlane_b32 s2, v253, 55
	v_readlane_b32 s3, v253, 56
	s_nop 4
	global_load_dword v7, v129, s[2:3] sc1
	v_readlane_b32 s2, v253, 57
	v_readlane_b32 s3, v253, 58
	s_nop 4
	global_load_dword v8, v129, s[2:3] sc1
	v_readlane_b32 s2, v253, 59
	v_readlane_b32 s3, v253, 60
	s_nop 4
	global_load_dword v9, v129, s[2:3] sc1
	v_readlane_b32 s2, v253, 61
	v_readlane_b32 s3, v253, 62
	s_nop 4
	global_load_dword v10, v129, s[2:3] sc1
	v_readlane_b32 s2, v253, 63
	v_readlane_b32 s3, v254, 0
	s_nop 4
	global_load_dword v11, v129, s[2:3] sc1
	v_readlane_b32 s2, v254, 1
	v_readlane_b32 s3, v254, 2
	s_nop 4
	global_load_dword v12, v129, s[2:3] sc1
	v_readlane_b32 s2, v254, 3
	v_readlane_b32 s3, v254, 4
	s_nop 4
	global_load_dword v13, v129, s[2:3] sc1
	v_readlane_b32 s2, v254, 5
	v_readlane_b32 s3, v254, 6
	s_nop 4
	global_load_dword v14, v129, s[2:3] sc1
	v_readlane_b32 s2, v254, 7
	v_readlane_b32 s3, v254, 8
	s_nop 4
	global_load_dword v15, v129, s[2:3] sc1
	s_mov_b64 s[2:3], -1
	s_waitcnt vmcnt(0)
	v_add_u32_e32 v16, v1, v0
	v_add_u32_e32 v16, v16, v2
	v_add_u32_e32 v16, v16, v3
	v_add_u32_e32 v16, v16, v4
	v_add_u32_e32 v16, v16, v5
	v_add_u32_e32 v16, v16, v6
	v_add_u32_e32 v16, v16, v7
	v_add_u32_e32 v16, v16, v8
	v_add_u32_e32 v16, v16, v9
	v_add_u32_e32 v16, v16, v10
	v_add_u32_e32 v16, v16, v11
	v_add_u32_e32 v16, v16, v12
	v_add_u32_e32 v16, v16, v13
	v_add_u32_e32 v16, v16, v14
	v_add_u32_e32 v16, v16, v15
	v_cmp_eq_u32_e32 vcc, s8, v16
	s_cbranch_vccnz .LBB0_581
	s_and_b32 s2, s9, 0xff
	s_cmp_eq_u32 s2, 0
	s_mov_b64 s[2:3], -1
	s_mov_b64 s[6:7], -1
	s_sleep 1
	s_cbranch_scc1 .LBB0_586
	s_and_b64 vcc, exec, s[6:7]
	s_cbranch_vccz .LBB0_581
